# v62 + no vmcnt(0) wait after the deferred-tile flag atomic (fire-and-forget signal)
# speedup vs baseline: 1.0016x; 1.0016x over previous
.Lko_nog:
	s_cmp_eq_u32 s100, 0
	s_cbranch_scc1 .Lko_nosig
	s_cmp_lt_u32 s62, 4
	s_cbranch_scc1 .Lko_nosig
	s_waitcnt vmcnt(0)
	s_barrier
	s_and_saveexec_b64 s[44:45], s[78:79]
	s_cbranch_execz .Lko_sigdone
	s_load_dwordx2 s[48:49], s[0:1], 0xe0
	buffer_wbl2 sc1
	s_lshl_b32 s4, s101, 6
	s_add_i32 s4, s4, s68
	s_lshl_b32 s4, s4, 2
	s_add_i32 s4, s4, s67
	s_sub_i32 s4, s4, 19
	s_lshl_b32 s4, s4, 2
	s_add_i32 s4, s4, 0x8000
	v_mov_b32_e32 v192, 0
	s_waitcnt vmcnt(0) lgkmcnt(0)
	s_add_u32 s48, s48, s4
	s_addc_u32 s49, s49, 0
	s_nop 4
	global_atomic_add v192, v252, s[48:49]
.Lko_sigdone:
	s_or_b64 exec, exec, s[44:45]
